# nt on the sample attention task's f32 key-cache loads
# baseline (speedup 1.0000x reference)
.LBB0_731:
	s_andn2_b64 vcc, exec, s[12:13]
	s_cbranch_vccnz .LBB0_722
	s_add_i32 s13, s14, s33
	s_and_b32 s14, s13, 3
	s_ashr_i32 s12, s13, 2
	s_and_b32 s13, s13, -4
	s_add_i32 s94, s13, 0x2000
	v_or_b32_e32 v96, s94, v125
	v_ashrrev_i32_e32 v97, 31, v96
	v_readlane_b32 s24, v254, 54
	v_lshl_or_b32 v103, s14, 3, v156
	v_lshlrev_b64 v[100:101], 12, v[96:97]
	v_readlane_b32 s25, v254, 55
	v_lshlrev_b32_e32 v130, 7, v103
	v_mov_b32_e32 v93, v131
	v_lshl_add_u64 v[0:1], s[24:25], 0, v[100:101]
	v_lshl_add_u64 v[0:1], v[0:1], 0, v[130:131]
	v_lshl_add_u64 v[0:1], v[0:1], 0, v[92:93]
	s_lshl_b32 s24, s14, 8
	s_mov_b32 s25, s92
	v_or_b32_e32 v4, s94, v136
	global_load_dwordx4 v[64:67], v[0:1], off
	global_load_dwordx4 v[88:91], v[0:1], off offset:32
	global_load_dwordx4 v[84:87], v[0:1], off offset:64
	global_load_dwordx4 v[80:83], v[0:1], off offset:96
	v_lshl_add_u64 v[0:1], v[140:141], 0, s[24:25]
	v_ashrrev_i32_e32 v5, 31, v4
	v_readlane_b32 s24, v254, 56
	s_lshl_b32 s13, s12, 7
	v_lshlrev_b64 v[4:5], 9, v[4:5]
	v_readlane_b32 s25, v254, 57
	v_or_b32_e32 v2, s13, v136
	v_ashrrev_i32_e32 v3, 31, v2
	v_lshl_add_u64 v[4:5], s[24:25], 0, v[4:5]
	s_lshl_b32 s24, s14, 7
	s_mov_b32 s25, s92
	v_lshl_add_u64 v[4:5], v[4:5], 0, s[24:25]
	v_lshl_add_u64 v[98:99], v[4:5], 0, v[92:93]
	v_lshlrev_b64 v[4:5], 10, v[2:3]
	v_lshl_add_u64 v[12:13], v[0:1], 0, v[4:5]
	global_load_dwordx4 v[4:7], v[12:13], off offset:16 nt
	global_load_dwordx4 v[8:11], v[12:13], off nt
	v_mov_b32_e32 v92, 0
	s_waitcnt vmcnt(0)
	v_cvt_pk_bf16_f32 v8, v8, v9
	v_cvt_pk_bf16_f32 v9, v10, v11
	v_cvt_pk_bf16_f32 v10, v4, v5
	v_cvt_pk_bf16_f32 v11, v6, v7
	s_nop 1
	v_mfma_f32_32x32x16_bf16 v[16:31], v[8:11], v[64:67], 0
	global_load_dwordx4 v[4:7], v[12:13], off offset:80 nt
	global_load_dwordx4 v[8:11], v[12:13], off offset:64 nt
	s_waitcnt vmcnt(0)
	v_cvt_pk_bf16_f32 v8, v8, v9
	v_cvt_pk_bf16_f32 v9, v10, v11
	v_cvt_pk_bf16_f32 v10, v4, v5
	v_cvt_pk_bf16_f32 v11, v6, v7
	s_nop 1
	v_mfma_f32_32x32x16_bf16 v[16:31], v[8:11], v[88:91], v[16:31]
	global_load_dwordx4 v[4:7], v[12:13], off offset:144 nt
	global_load_dwordx4 v[8:11], v[12:13], off offset:128 nt
	s_waitcnt vmcnt(0)
	v_cvt_pk_bf16_f32 v8, v8, v9
	v_cvt_pk_bf16_f32 v9, v10, v11
	v_cvt_pk_bf16_f32 v10, v4, v5
	v_cvt_pk_bf16_f32 v11, v6, v7
	s_nop 1
	v_mfma_f32_32x32x16_bf16 v[16:31], v[8:11], v[84:87], v[16:31]
	global_load_dwordx4 v[4:7], v[12:13], off offset:208 nt
	global_load_dwordx4 v[8:11], v[12:13], off offset:192 nt
	s_waitcnt vmcnt(0)
	v_cvt_pk_bf16_f32 v8, v8, v9
	v_cvt_pk_bf16_f32 v9, v10, v11
	v_cvt_pk_bf16_f32 v10, v4, v5
	v_cvt_pk_bf16_f32 v11, v6, v7
	v_or_b32_e32 v4, 32, v2
	v_ashrrev_i32_e32 v5, 31, v4
	v_lshlrev_b64 v[4:5], 10, v[4:5]
	v_lshl_add_u64 v[12:13], v[0:1], 0, v[4:5]
	v_mfma_f32_32x32x16_bf16 v[16:31], v[8:11], v[80:83], v[16:31]
	global_load_dwordx4 v[4:7], v[12:13], off offset:16 nt
	global_load_dwordx4 v[8:11], v[12:13], off nt
	s_waitcnt vmcnt(0)
	v_cvt_pk_bf16_f32 v8, v8, v9
	v_cvt_pk_bf16_f32 v9, v10, v11
	v_cvt_pk_bf16_f32 v10, v4, v5
	v_cvt_pk_bf16_f32 v11, v6, v7
	s_nop 1
	v_mfma_f32_32x32x16_bf16 v[32:47], v[8:11], v[64:67], 0
	global_load_dwordx4 v[4:7], v[12:13], off offset:80 nt
	global_load_dwordx4 v[8:11], v[12:13], off offset:64 nt
	s_waitcnt vmcnt(0)
	v_cvt_pk_bf16_f32 v8, v8, v9
	v_cvt_pk_bf16_f32 v9, v10, v11
	v_cvt_pk_bf16_f32 v10, v4, v5
	v_cvt_pk_bf16_f32 v11, v6, v7
	s_nop 1
	v_mfma_f32_32x32x16_bf16 v[32:47], v[8:11], v[88:91], v[32:47]
	global_load_dwordx4 v[4:7], v[12:13], off offset:144 nt
	global_load_dwordx4 v[8:11], v[12:13], off offset:128 nt
	s_waitcnt vmcnt(0)
	v_cvt_pk_bf16_f32 v8, v8, v9
	v_cvt_pk_bf16_f32 v9, v10, v11
	v_cvt_pk_bf16_f32 v10, v4, v5
	v_cvt_pk_bf16_f32 v11, v6, v7
	s_nop 1
	v_mfma_f32_32x32x16_bf16 v[32:47], v[8:11], v[84:87], v[32:47]
	global_load_dwordx4 v[4:7], v[12:13], off offset:208 nt
	global_load_dwordx4 v[8:11], v[12:13], off offset:192 nt
	s_waitcnt vmcnt(0)
	v_cvt_pk_bf16_f32 v8, v8, v9
	v_cvt_pk_bf16_f32 v9, v10, v11
	v_cvt_pk_bf16_f32 v10, v4, v5
	v_cvt_pk_bf16_f32 v11, v6, v7
	v_or_b32_e32 v4, 64, v2
	v_ashrrev_i32_e32 v5, 31, v4
	v_lshlrev_b64 v[4:5], 10, v[4:5]
	v_lshl_add_u64 v[12:13], v[0:1], 0, v[4:5]
	v_mfma_f32_32x32x16_bf16 v[32:47], v[8:11], v[80:83], v[32:47]
	global_load_dwordx4 v[4:7], v[12:13], off offset:16 nt
	global_load_dwordx4 v[8:11], v[12:13], off nt
	v_or_b32_e32 v2, 0x60, v2
	v_ashrrev_i32_e32 v3, 31, v2
	v_lshlrev_b64 v[2:3], 10, v[2:3]
	v_lshl_add_u64 v[76:77], v[0:1], 0, v[2:3]
	s_waitcnt vmcnt(0)
	v_cvt_pk_bf16_f32 v8, v8, v9
	v_cvt_pk_bf16_f32 v9, v10, v11
	v_cvt_pk_bf16_f32 v10, v4, v5
	v_cvt_pk_bf16_f32 v11, v6, v7
	s_nop 1
	v_mfma_f32_32x32x16_bf16 v[48:63], v[8:11], v[64:67], 0
	global_load_dwordx4 v[4:7], v[12:13], off offset:80 nt
	global_load_dwordx4 v[8:11], v[12:13], off offset:64 nt
	s_waitcnt vmcnt(0)
	v_cvt_pk_bf16_f32 v8, v8, v9
	v_cvt_pk_bf16_f32 v9, v10, v11
	v_cvt_pk_bf16_f32 v10, v4, v5
	v_cvt_pk_bf16_f32 v11, v6, v7
	s_nop 1
	v_mfma_f32_32x32x16_bf16 v[48:63], v[8:11], v[88:91], v[48:63]
	global_load_dwordx4 v[4:7], v[12:13], off offset:144 nt
	global_load_dwordx4 v[8:11], v[12:13], off offset:128 nt
	s_waitcnt vmcnt(0)
	v_cvt_pk_bf16_f32 v8, v8, v9
	v_cvt_pk_bf16_f32 v9, v10, v11
	v_cvt_pk_bf16_f32 v10, v4, v5
	v_cvt_pk_bf16_f32 v11, v6, v7
	s_nop 1
	v_mfma_f32_32x32x16_bf16 v[48:63], v[8:11], v[84:87], v[48:63]
	global_load_dwordx4 v[4:7], v[12:13], off offset:208 nt
	global_load_dwordx4 v[8:11], v[12:13], off offset:192 nt
	s_waitcnt vmcnt(0)
	v_cvt_pk_bf16_f32 v8, v8, v9
	v_cvt_pk_bf16_f32 v9, v10, v11
	v_cvt_pk_bf16_f32 v10, v4, v5
	v_cvt_pk_bf16_f32 v11, v6, v7
	global_load_dwordx4 v[0:3], v[76:77], off offset:16 nt
	global_load_dwordx4 v[4:7], v[76:77], off nt
	global_load_dwordx4 v[68:71], v[76:77], off offset:80 nt
	global_load_dwordx4 v[72:75], v[76:77], off offset:64 nt
	v_mfma_f32_32x32x16_bf16 v[48:63], v[8:11], v[80:83], v[48:63]
	s_waitcnt vmcnt(2)
	v_cvt_pk_bf16_f32 v4, v4, v5
	v_cvt_pk_bf16_f32 v5, v6, v7
	v_cvt_pk_bf16_f32 v6, v0, v1
	v_cvt_pk_bf16_f32 v7, v2, v3
	s_waitcnt vmcnt(0)
	v_cvt_pk_bf16_f32 v72, v72, v73
	v_cvt_pk_bf16_f32 v73, v74, v75
	v_mfma_f32_32x32x16_bf16 v[0:15], v[4:7], v[64:67], 0
	v_cvt_pk_bf16_f32 v74, v68, v69
	v_cvt_pk_bf16_f32 v75, v70, v71
	s_nop 1
	v_mfma_f32_32x32x16_bf16 v[0:15], v[72:75], v[88:91], v[0:15]
	global_load_dwordx4 v[68:71], v[76:77], off offset:144 nt
	global_load_dwordx4 v[72:75], v[76:77], off offset:128 nt
	s_waitcnt vmcnt(0)
	v_cvt_pk_bf16_f32 v72, v72, v73
	v_cvt_pk_bf16_f32 v73, v74, v75
	v_cvt_pk_bf16_f32 v74, v68, v69
	v_cvt_pk_bf16_f32 v75, v70, v71
	s_nop 1
	v_mfma_f32_32x32x16_bf16 v[0:15], v[72:75], v[84:87], v[0:15]
	global_load_dwordx4 v[68:71], v[76:77], off offset:208 nt
	global_load_dwordx4 v[72:75], v[76:77], off offset:192 nt
	s_waitcnt vmcnt(0)
	v_cvt_pk_bf16_f32 v72, v72, v73
	v_cvt_pk_bf16_f32 v73, v74, v75
	v_cvt_pk_bf16_f32 v74, v68, v69
	v_cvt_pk_bf16_f32 v75, v70, v71
	v_mov_b32_e32 v68, 0
	v_mov_b32_e32 v69, 0
	v_mfma_f32_32x32x16_bf16 v[0:15], v[72:75], v[80:83], v[0:15]
	v_mov_b32_e32 v70, 0
	v_mov_b32_e32 v71, 0
	s_and_saveexec_b64 vcc, s[42:43]
	s_cbranch_execz .LBB0_734
	global_load_dwordx4 v[68:71], v[98:99], off
